# scan: copy-1 prefetch wait placed before the conditional ssq store so it no longer drains the Y store ack
# baseline (speedup 1.0000x reference)
; #define LAS __attribute__((address_space(3)))
; template <bool DRY>
; __device__ __forceinline__ void ssd_chunk(SsdRegs& R, f32x4 (&st)[2], LAS unsigned char* L, bf16_t* BIG, const float* DT, float* SSQY, const SsdItem& I, int c, int tid, int lane, int wave, int li, int pi, int c16, int q4) {
;     ...
;     float acs = dtl * I.Ah;
;     acs += dppz<0x111>(acs); acs += dppz<0x112>(acs); acs += dppz<0x114>(acs); acs += dppz<0x118>(acs);
;     ...
;     for (int kk = 0; kk < 2; ++kk) { bwf[kk] = SSD_TR(BW, PB, trB, wave, kk); xfr[0][kk] = SSD_TR(XI, PX, trX, 0, kk); xfr[1][kk] = SSD_TR(XI, PX, trX, 1, kk); }
; #pragma unroll
;     for (int pt = 0; pt < 2; ++pt) {
;         f32x4 d = st[pt] * etot;
; #pragma unroll
;         for (int kk = 0; kk < 2; ++kk) d = __builtin_amdgcn_mfma_f32_16x16x32_bf16(bwf[kk], xfr[pt][kk], d, 0, 0, 0);
;         stn[pt] = d;
;     }
;     const bf16x8 xy0 = pi ? xfr[1][0] : xfr[0][0], xy1 = pi ? xfr[1][1] : xfr[0][1];
;     st[0] = stn[0]; st[1] = stn[1];
;     __syncthreads();
;     {
;         f32x4 d1 = (f32x4){0.f, 0.f, 0.f, 0.f}, d2 = (f32x4){0.f, 0.f, 0.f, 0.f};
; #pragma unroll
;         for (int kk = 0; kk < 2; ++kk) d1 = __builtin_amdgcn_mfma_f32_16x16x32_bf16(kk ? xy1 : xy0, SSD_FRAG(GG, PT, 16 * li, kk), d1, 0, 0, 0);
; #pragma unroll
;         for (int kk = 0; kk < 4; ++kk) d2 = __builtin_amdgcn_mfma_f32_16x16x32_bf16(SSD_FRAG(SB, PC, 16 * pi, kk), cfr[kk], d2, 0, 0, 0);
;         const int l = 16 * li + c16; const float ea_l = __expf(*(const LAS float*)(SCW + l * 4));
;         const float zf[4] = {bf_lo(zc.x), bf_hi(zc.x), bf_lo(zc.y), bf_hi(zc.y)};
;         float yg[4], sq = 0.f;
;         const u32x2 xr = *(const LAS u32x2*)(L + XI + l * PX + (16 * pi + 4 * q4) * 2);
;         const float xs[4] = {bf_lo(xr.x), bf_hi(xr.x), bf_lo(xr.y), bf_hi(xr.y)};
; #pragma unroll
;         for (int e = 0; e < 4; ++e) { const float xv = xs[e];
;             const float y = d1[e] + ea_l * d2[e] + I.Dh * xv; yg[e] = y * silu_f(zf[e]); sq += yg[e] * yg[e]; }
;         u32x2 w; w.x = pk2(yg[0], yg[1]); w.y = pk2(yg[2], yg[3]);
;         if (!DRY) *(u32x2*)((char*)BIG + row0 * (BIGW * 2) + I.offZ) = w;
;         sq += __shfl_xor(sq, 16); sq += __shfl_xor(sq, 32);
;         if (DRY) { if (sq == 12345.678f) SSQY[0] = 1.f; } else if (q4 == 0) SSQY[(size_t)(I.h * 4 + I.ph * 2 + pi) * M_ + row0 + l] = sq;
.LBB0_733:
	v_add_u32_e32 v145, s69, v113
	s_waitcnt lgkmcnt(1)
	ds_write_b64 v145, v[106:107]
	ds_read_b64_tr_b16 v[146:147], v194 offset:17408
	ds_read_b64_tr_b16 v[148:149], v194 offset:18496
	v_exp_f32_e32 v76, s3
	ds_read_b64_tr_b16 v[152:153], v138 offset:35200
	ds_read_b64_tr_b16 v[150:151], v138 offset:34816
	ds_read_b64_tr_b16 v[154:155], v194 offset:26112
	ds_read_b64_tr_b16 v[156:157], v194 offset:27200
	ds_read_b64_tr_b16 v[158:159], v138 offset:37888
	ds_read_b64_tr_b16 v[160:161], v138 offset:38272
	ds_read_b64_tr_b16 v[162:163], v138 offset:34848
	ds_read_b64_tr_b16 v[164:165], v138 offset:35232
	ds_read_b64_tr_b16 v[166:167], v138 offset:37920
	ds_read_b64_tr_b16 v[168:169], v138 offset:38304
	v_pk_mul_f32 v[52:53], v[52:53], v[76:77] op_sel_hi:[1,0]
	v_pk_mul_f32 v[50:51], v[50:51], v[76:77] op_sel_hi:[1,0]
	v_pk_mul_f32 v[56:57], v[56:57], v[76:77] op_sel_hi:[1,0]
	v_pk_mul_f32 v[54:55], v[54:55], v[76:77] op_sel_hi:[1,0]
	s_waitcnt lgkmcnt(8)
	v_mfma_f32_16x16x32_bf16 v[50:53], v[146:149], v[150:153], v[50:53]
	ds_read_b64_tr_b16 v[196:197], v83 offset:53248
	ds_read_b64_tr_b16 v[198:199], v83 offset:53632
	ds_read_b64_tr_b16 v[200:201], v83 offset:56320
	ds_read_b64_tr_b16 v[202:203], v83 offset:56704
	v_add_u32_e32 v143, v112, v111
	s_waitcnt lgkmcnt(0)
	s_barrier
	v_mfma_f32_16x16x32_bf16 v[54:57], v[146:149], v[162:165], v[54:57]
	v_mfma_f32_16x16x32_bf16 v[50:53], v[154:157], v[158:161], v[50:53]
	v_mfma_f32_16x16x32_bf16 v[54:57], v[154:157], v[166:169], v[54:57]
	ds_read_b128 v[150:153], v143
	ds_read_b128 v[154:157], v123
	ds_read_b32 v76, v132
	s_waitcnt lgkmcnt(2)
	v_mfma_f32_16x16x32_bf16 v[146:149], v[196:199], v[150:153], 0
	ds_read_b128 v[150:153], v123 offset:64
	s_waitcnt lgkmcnt(2)
	v_mfma_f32_16x16x32_bf16 v[70:73], v[154:157], v[70:73], 0
	ds_read_b128 v[154:157], v123 offset:128
	s_waitcnt lgkmcnt(1)
	v_mfma_f32_16x16x32_bf16 v[66:69], v[150:153], v[66:69], v[70:73]
	s_nop 4
	ds_read_b128 v[70:73], v123 offset:192
	s_waitcnt lgkmcnt(1)
	v_mfma_f32_16x16x32_bf16 v[62:65], v[154:157], v[62:65], v[66:69]
	s_nop 2
	ds_read_b128 v[66:69], v143 offset:64
	s_waitcnt lgkmcnt(1)
	v_mfma_f32_16x16x32_bf16 v[58:61], v[70:73], v[58:61], v[62:65]
	v_lshlrev_b32_e32 v70, 16, v96
	s_nop 1
	v_exp_f32_e32 v72, v76
	v_mul_f32_e32 v62, 0xbfb8aa3b, v70
	v_exp_f32_e32 v71, v62
	s_waitcnt lgkmcnt(0)
	v_mfma_f32_16x16x32_bf16 v[62:65], v[200:203], v[66:69], v[146:149]
	ds_read_b64 v[66:67], v139 offset:53248
	s_nop 6
	v_fma_f32 v62, v58, v72, v62
	v_add_f32_e32 v58, 1.0, v71
	v_rcp_f32_e32 v76, v58
	v_and_b32_e32 v58, 0xffff0000, v96
	v_mul_f32_e32 v68, 0xbfb8aa3b, v58
	v_exp_f32_e32 v73, v68
	s_waitcnt lgkmcnt(0)
	v_lshlrev_b32_e32 v71, 16, v66
	v_pk_mul_f32 v[68:69], v[76:77], v[70:71]
	v_fma_f32 v63, v59, v72, v63
	v_add_f32_e32 v62, v62, v69
	v_add_f32_e32 v69, 1.0, v73
	v_rcp_f32_e32 v76, v69
	v_and_b32_e32 v59, 0xffff0000, v66
	v_mul_f32_e32 v62, v68, v62
	v_fma_f32 v64, v60, v72, v64
	v_pk_mul_f32 v[58:59], v[76:77], v[58:59]
	v_fmac_f32_e32 v65, v61, v72
	v_add_f32_e32 v59, v63, v59
	v_mul_f32_e32 v63, v58, v59
	v_lshlrev_b32_e32 v58, 16, v97
	v_mul_f32_e32 v59, 0xbfb8aa3b, v58
	v_exp_f32_e32 v68, v59
	v_lshlrev_b32_e32 v59, 16, v67
	v_and_b32_e32 v61, 0xffff0000, v67
	v_mul_f32_e32 v66, v63, v63
	v_add_f32_e32 v60, 1.0, v68
	v_rcp_f32_e32 v76, v60
	v_and_b32_e32 v60, 0xffff0000, v97
	v_mul_f32_e32 v68, 0xbfb8aa3b, v60
	v_exp_f32_e32 v68, v68
	v_pk_mul_f32 v[58:59], v[76:77], v[58:59]
	v_fmac_f32_e32 v66, v62, v62
	v_add_f32_e32 v59, v64, v59
	v_mul_f32_e32 v64, v58, v59
	v_add_f32_e32 v58, 1.0, v68
	v_rcp_f32_e32 v76, v58
	v_fmac_f32_e32 v66, v64, v64
	v_pk_mul_f32 v[58:59], v[76:77], v[60:61]
	s_nop 0
	v_add_f32_e32 v59, v65, v59
	v_mul_f32_e32 v58, v58, v59
	v_fmac_f32_e32 v66, v58, v58
	v_mov_b32_e32 v59, v66
	v_cvt_pk_bf16_f32 v60, v62, v63
	v_cvt_pk_bf16_f32 v61, v64, v58
	v_permlane16_swap_b32 v59, v66
	global_store_dwordx2 v[78:79], v[60:61], off
	s_waitcnt vmcnt(1)
	v_add_f32_e32 v58, v66, v59
	v_mov_b32_e32 v59, v58
	s_mov_b64 s[0:1], 0xc0000
	v_lshl_add_u64 v[78:79], v[78:79], 0, s[0:1]
	s_nop 0
	v_permlane32_swap_b32 v59, v58
	s_and_saveexec_b64 s[0:1], s[18:19]
	s_cbranch_execz .LBB0_735
	v_add_f32_e32 v60, v58, v59
	global_store_dword v[90:91], v60, off
.LBB0_735:
	s_or_b64 exec, exec, s[0:1]
	v_mul_f32_e64 v58, v2, -v141
	s_waitcnt lgkmcnt(0)
	v_mov_b32_e32 v59, 0
	s_nop 0
	v_mov_b32_dpp v58, v58 row_shr:1 row_mask:0xf bank_mask:0xf bound_ctrl:1
	v_fma_f32 v58, v2, -v141, v58
	s_nop 0
	s_nop 0
	v_add_f32_dpp v58, v58, v58 row_shr:2 row_mask:0xf bank_mask:0xf bound_ctrl:1
	s_nop 0
	s_nop 0
	v_add_f32_dpp v58, v58, v58 row_shr:4 row_mask:0xf bank_mask:0xf bound_ctrl:1
	s_and_b64 vcc, exec, s[20:21]
	s_nop 0
	v_add_f32_dpp v58, v58, v58 row_shr:8 row_mask:0xf bank_mask:0xf bound_ctrl:1
	s_nop 1
	v_mov_b32_dpp v59, v58 row_bcast:15 row_mask:0xa bank_mask:0xf
	v_add_f32_e32 v58, v58, v59
	v_mov_b32_e32 v59, 0
	s_nop 1
	v_mov_b32_dpp v59, v58 row_bcast:31 row_mask:0xc bank_mask:0xf
	v_add_f32_e32 v58, v58, v59
	ds_write2st64_b32 v126, v58, v2 offset1:1
	v_readlane_b32 s3, v58, 63
	s_nop 1
	v_sub_f32_e32 v59, s3, v58
	v_exp_f32_e32 v60, v59
	v_cvt_pk_bf16_f32 v58, v50, v51
	v_cvt_pk_bf16_f32 v59, v52, v53
	ds_write_b64 v124, v[58:59]
	v_cvt_pk_bf16_f32 v58, v54, v55
	v_cvt_pk_bf16_f32 v59, v56, v57
	ds_write_b64 v124, v[58:59] offset:4352
	ds_write_b128 v127, v[34:37]
	ds_write_b128 v127, v[30:33] offset:17408
	v_mul_f32_e32 v62, v2, v60
	ds_write_b128 v129, v[46:49]
	ds_write_b128 v129, v[42:45] offset:17408
	s_cbranch_vccnz .LBB0_737
	ds_bpermute_b32 v82, v195, v62
	ds_write_b128 v130, v[38:41] offset:59392
	v_lshlrev_b32_e32 v58, 16, v38
	v_and_b32_e32 v59, 0xffff0000, v38
	v_lshlrev_b32_e32 v60, 16, v39
	v_and_b32_e32 v61, 0xffff0000, v39
	v_lshlrev_b32_e32 v64, 16, v40
	v_and_b32_e32 v65, 0xffff0000, v40
	v_lshlrev_b32_e32 v66, 16, v41
	v_and_b32_e32 v67, 0xffff0000, v41
	s_waitcnt lgkmcnt(1)
	v_pk_mul_f32 v[58:59], v[58:59], v[82:83] op_sel_hi:[1,0]
	v_pk_mul_f32 v[60:61], v[60:61], v[82:83] op_sel_hi:[1,0]
	v_pk_mul_f32 v[64:65], v[64:65], v[82:83] op_sel_hi:[1,0]
	v_pk_mul_f32 v[66:67], v[66:67], v[82:83] op_sel_hi:[1,0]
	v_cvt_pk_bf16_f32 v58, v58, v59
	v_cvt_pk_bf16_f32 v59, v60, v61
	v_cvt_pk_bf16_f32 v60, v64, v65
	v_cvt_pk_bf16_f32 v61, v66, v67
	ds_write_b128 v130, v[58:61] offset:34816
